# weight-conversion jobs processed in reverse order so the matrices the next phase re-reads first (FFN-in, QKV) are the most recently touched (cache residency)
# speedup vs baseline: 1.4048x; 1.4048x over previous
.LBB0_33:
	s_mul_i32 s0, s17, 40
	s_sub_i32 s0, 0x280, s0
	v_readlane_b32 s4, v253, 2
	s_mul_hi_u32 s1, s17, 40
	v_readlane_b32 s5, v253, 3
	s_add_u32 s0, s4, s0
	s_addc_u32 s1, s5, s1
	s_load_dwordx4 s[4:7], s[0:1], 0xd8
	s_waitcnt lgkmcnt(0)
	s_ashr_i32 s20, s6, 6
	s_ashr_i32 s7, s7, 7
	s_mov_b32 s38, s7
	s_mul_i32 s7, s7, s20
	s_cmp_ge_i32 s16, s7
	s_cbranch_scc1 .LBB0_32
	s_abs_i32 s26, s38
	v_cvt_f32_u32_e32 v2, s26
	s_load_dword s27, s[0:1], 0xe8
	s_load_dwordx4 s[8:11], s[0:1], 0xc8
	s_lshl_b32 s0, s20, 6
	s_sub_i32 s1, 0, s26
	v_rcp_iflag_f32_e32 v2, v2
	s_sub_i32 s30, 0, s0
	s_ashr_i32 s28, s38, 31
	s_mov_b32 s29, s19
	v_mul_f32_e32 v2, 0x4f7ffffe, v2
	v_cvt_u32_f32_e32 v2, v2
	s_mov_b32 s33, s16
	v_readfirstlane_b32 s0, v2
	s_mul_i32 s1, s1, s0
	s_mul_hi_u32 s1, s0, s1
	s_add_i32 s31, s0, s1
	s_branch .LBB0_36
